# static s_setprio 1 for the wave-slot-0 wave of each SIMD during the FoX attention phase (reset after the phase barrier)
# speedup vs baseline: 1.0060x; 1.0060x over previous
.LBB0_547:
	s_ashr_i32 s3, s2, 31
	s_lshl_b64 s[0:1], s[2:3], 3
	v_readlane_b32 s2, v254, 0
	v_readlane_b32 s3, v254, 1
	s_add_u32 s0, s2, s0
	s_addc_u32 s1, s3, s1
	s_load_dwordx2 s[0:1], s[0:1], 0x100
	s_mov_b32 s20, 0
	s_mov_b32 s21, s19
	s_waitcnt lgkmcnt(0)
	s_add_u32 s22, s0, 0xb600a00
	s_addc_u32 s24, s1, 0
	s_add_u32 s25, s0, 0xb600c00
	s_addc_u32 s28, s1, 0
	s_add_u32 s29, s0, 0xb600e00
	s_addc_u32 s38, s1, 0
	s_add_u32 s39, s0, 0x10f60400
	s_addc_u32 s40, s1, 0
	s_add_u32 s41, s0, 0x3580000
	s_addc_u32 s42, s1, 0
	s_mov_b32 s0, s19
	s_getreg_b32 s100, hwreg(HW_REG_HW_ID, 0, 4)
	s_cmp_lg_u32 s100, 0
	s_cbranch_scc1 .Lattn_prio_done
	s_setprio 1
.Lattn_prio_done:
	s_branch .LBB0_549

.LBB0_839:
	s_or_b64 exec, exec, s[2:3]
	s_waitcnt lgkmcnt(0)
	s_barrier
	s_setprio 0
